# attention: permlane32_swap row-max exchange plus skip of redundant score-accumulator zero-init on fully-past key tiles
# speedup vs baseline: 1.0042x; 1.0008x over previous
; DI void attn_item(const Params& p, int l, int b, int head, int qt, float lam, float lam_init, unsigned char* smem) {
;     ...
;     if (active && kt < my_nkt) {
;       const unsigned char* Kt = sb + (j & 1) * AT_STAGE;
;       const unsigned char* Vt = Kt + AT_KBYTES;
;       f32x16 s[2];
;       const bool past = (kt * 64 + 63) < (qpos0 + rg * 32);
;       if (past) {
;         const float kb0 = slope2 * (float)(kt * 64 + 4 * h);
; #pragma unroll
;         for (int sub = 0; sub < 2; ++sub)
; #pragma unroll
;           for (int i = 0; i < 16; ++i) s[sub][i] = __builtin_fmaf(slope2, (float)(sub * 32 + (i & 3) + 8 * (i >> 2)), kb0);
;       } else {
;         zero16(s[0]); zero16(s[1]);
;       }
.LBB0_475:
	v_cmp_lt_i32_e32 vcc, s13, v183
	s_and_saveexec_b64 s[6:7], vcc
	s_cbranch_execz .LBB0_484
	s_add_i32 s0, s14, 63
	v_mov_b32_e32 v80, 0
	v_cmp_ge_i32_e32 vcc, s0, v135
	v_cmp_lt_i32_e64 s[0:1], s0, v135
	s_nop 1
	s_xor_b64 s[8:9], s[0:1], exec
	s_cmp_eq_u64 s[8:9], 0
	s_cbranch_scc1 .Lattn_pastfast
	v_mov_b32_e32 v81, v80
	v_mov_b32_e32 v82, v80
	v_mov_b32_e32 v83, v80
	v_mov_b32_e32 v84, v80
	v_mov_b32_e32 v85, v80
	v_mov_b32_e32 v86, v80
	v_mov_b32_e32 v87, v80
	v_mov_b32_e32 v88, v80
	v_mov_b32_e32 v89, v80
	v_mov_b32_e32 v90, v80
	v_mov_b32_e32 v91, v80
	v_mov_b32_e32 v92, v80
	v_mov_b32_e32 v93, v80
	v_mov_b32_e32 v94, v80
	v_mov_b32_e32 v95, v80
	v_mov_b32_e32 v64, v80
	v_mov_b32_e32 v65, v80
	v_mov_b32_e32 v66, v80
	v_mov_b32_e32 v67, v80
	v_mov_b32_e32 v68, v80
	v_mov_b32_e32 v69, v80
	v_mov_b32_e32 v70, v80
	v_mov_b32_e32 v71, v80
	v_mov_b32_e32 v72, v80
	v_mov_b32_e32 v73, v80
	v_mov_b32_e32 v74, v80
	v_mov_b32_e32 v75, v80
	v_mov_b32_e32 v76, v80
	v_mov_b32_e32 v77, v80
	v_mov_b32_e32 v78, v80
	v_mov_b32_e32 v79, v80
.Lattn_pastfast:
	s_and_saveexec_b64 s[8:9], s[0:1]
	s_cbranch_execz .LBB0_478
	v_add_u32_e32 v64, s14, v133
	v_cvt_f32_i32_e32 v64, v64
	s_mov_b32 s0, 2.0
	s_mov_b32 s1, 0x40400000
	v_mul_f32_e32 v78, v140, v64
	v_pk_fma_f32 v[82:83], v[140:141], s[0:1], v[78:79] op_sel_hi:[1,1,0]
	s_mov_b32 s0, 0x41000000
	s_mov_b32 s1, 0x41100000
	v_pk_fma_f32 v[84:85], v[140:141], s[0:1], v[78:79] op_sel_hi:[1,1,0]
	s_mov_b32 s0, 0x41200000
	s_mov_b32 s1, 0x41300000
	v_pk_fma_f32 v[86:87], v[140:141], s[0:1], v[78:79] op_sel_hi:[1,1,0]
	s_mov_b32 s0, 0x41800000
	s_mov_b32 s1, 0x41880000
	v_pk_fma_f32 v[88:89], v[140:141], s[0:1], v[78:79] op_sel_hi:[1,1,0]
	s_mov_b32 s0, 0x41900000
	s_mov_b32 s1, 0x41980000
	v_pk_fma_f32 v[90:91], v[140:141], s[0:1], v[78:79] op_sel_hi:[1,1,0]
	s_mov_b32 s0, 0x41c00000
	s_mov_b32 s1, 0x41c80000
	v_pk_fma_f32 v[92:93], v[140:141], s[0:1], v[78:79] op_sel_hi:[1,1,0]
	s_mov_b32 s0, 0x41d00000
	s_mov_b32 s1, 0x41d80000
	v_pk_fma_f32 v[94:95], v[140:141], s[0:1], v[78:79] op_sel_hi:[1,1,0]
	s_mov_b32 s0, 0x42000000
	s_mov_b32 s1, 0x42040000
	v_fma_f32 v81, v140, v64, v140
	v_pk_fma_f32 v[64:65], v[140:141], s[0:1], v[78:79] op_sel_hi:[1,1,0]
	s_mov_b32 s0, 0x42080000
	s_mov_b32 s1, 0x420c0000
	v_pk_fma_f32 v[66:67], v[140:141], s[0:1], v[78:79] op_sel_hi:[1,1,0]
	s_mov_b32 s0, 0x42200000
	s_mov_b32 s1, 0x42240000
	v_pk_fma_f32 v[68:69], v[140:141], s[0:1], v[78:79] op_sel_hi:[1,1,0]
	s_mov_b32 s0, 0x42280000
	s_mov_b32 s1, 0x422c0000
	v_pk_fma_f32 v[70:71], v[140:141], s[0:1], v[78:79] op_sel_hi:[1,1,0]
	s_mov_b32 s0, 0x42400000
	s_mov_b32 s1, 0x42440000
	v_pk_fma_f32 v[72:73], v[140:141], s[0:1], v[78:79] op_sel_hi:[1,1,0]
	s_mov_b32 s0, 0x42480000
	s_mov_b32 s1, 0x424c0000
	v_pk_fma_f32 v[74:75], v[140:141], s[0:1], v[78:79] op_sel_hi:[1,1,0]
	s_mov_b32 s0, 0x42600000
	s_mov_b32 s1, 0x42640000
	v_pk_fma_f32 v[76:77], v[140:141], s[0:1], v[78:79] op_sel_hi:[1,1,0]
	s_mov_b32 s0, 0x42680000
	v_mov_b32_e32 v80, v78
	s_mov_b32 s1, 0x426c0000
	v_fmac_f32_e32 v80, 0, v140
	v_pk_fma_f32 v[78:79], v[140:141], s[0:1], v[78:79] op_sel_hi:[1,1,0]
